# top-k bisection: prefix search downward from the row maximum (up to 4 counting passes) before the bitwise loop, else unchanged loop
# speedup vs baseline: 1.2746x; 1.0072x over previous
.LBB0_890:
	s_or_b64 exec, exec, s[0:1]
	v_readlane_b32 s0, v254, 51
	v_readlane_b32 s4, v254, 29
	s_lshl_b32 s0, s0, 8
	v_readlane_b32 s18, v254, 43
	v_and_b32_e32 v16, 63, v43
	v_readlane_b32 s1, v254, 52
	v_readlane_b32 s19, v254, 44
	s_add_u32 s0, s18, s0
	v_ashrrev_i32_e32 v43, 31, v42
	s_addc_u32 s1, s19, 0
	v_mul_u32_u24_e32 v2, 0x4100, v47
	v_lshlrev_b64 v[0:1], 8, v[42:43]
	v_lshlrev_b32_e32 v3, 2, v16
	v_lshl_add_u64 v[0:1], s[0:1], 0, v[0:1]
	s_cmpk_lt_u32 s71, 0xc00
	s_waitcnt vmcnt(3)
	v_add3_u32 v28, v46, v2, v3
	v_readlane_b32 s5, v254, 30
	v_readlane_b32 s6, v254, 31
	v_readlane_b32 s7, v254, 32
	v_readlane_b32 s8, v254, 33
	v_readlane_b32 s9, v254, 34
	v_readlane_b32 s10, v254, 35
	v_readlane_b32 s11, v254, 36
	v_readlane_b32 s12, v254, 37
	v_readlane_b32 s13, v254, 38
	v_readlane_b32 s14, v254, 39
	v_readlane_b32 s15, v254, 40
	v_readlane_b32 s16, v254, 41
	v_readlane_b32 s17, v254, 42
	s_waitcnt lgkmcnt(0)
	s_barrier
	s_cbranch_scc0 .LBB0_1038
	s_cmpk_lt_u32 s71, 0x800
	s_cbranch_scc0 .LBB0_1043
	s_cmpk_lt_u32 s71, 0x400
	s_cbranch_scc0 .LBB0_1044
	ds_read2st64_b32 v[26:27], v28 offset1:1
	ds_read2st64_b32 v[24:25], v28 offset0:2 offset1:3
	ds_read2st64_b32 v[22:23], v28 offset0:4 offset1:5
	ds_read2st64_b32 v[20:21], v28 offset0:6 offset1:7
	ds_read2st64_b32 v[18:19], v28 offset0:8 offset1:9
	ds_read2st64_b32 v[14:15], v28 offset0:10 offset1:11
	ds_read2st64_b32 v[12:13], v28 offset0:12 offset1:13
	ds_read2st64_b32 v[10:11], v28 offset0:14 offset1:15
	ds_read2st64_b32 v[8:9], v28 offset0:16 offset1:17
	ds_read2st64_b32 v[6:7], v28 offset0:18 offset1:19
	ds_read2st64_b32 v[4:5], v28 offset0:20 offset1:21
	ds_read2st64_b32 v[2:3], v28 offset0:22 offset1:23
	v_or_b32_e32 v29, 0x600, v16
	v_cmp_gt_u32_e32 vcc, s72, v29
	s_waitcnt vmcnt(1)
	v_mov_b32_e32 v36, 0
	v_mov_b32_e32 v37, 0
	s_and_saveexec_b64 s[0:1], vcc
	ds_read_b32 v37, v28 offset:6144
	s_or_b64 exec, exec, s[0:1]
	v_or_b32_e32 v29, 0x640, v16
	v_cmp_gt_u32_e32 vcc, s72, v29
	s_and_saveexec_b64 s[0:1], vcc
	ds_read_b32 v36, v28 offset:6400
	s_or_b64 exec, exec, s[0:1]
	v_or_b32_e32 v29, 0x680, v16
	v_cmp_gt_u32_e32 vcc, s72, v29
	v_mov_b32_e32 v34, 0
	v_mov_b32_e32 v35, 0
	s_and_saveexec_b64 s[0:1], vcc
	ds_read_b32 v35, v28 offset:6656
	s_or_b64 exec, exec, s[0:1]
	v_or_b32_e32 v29, 0x6c0, v16
	v_cmp_gt_u32_e32 vcc, s72, v29
	s_and_saveexec_b64 s[0:1], vcc
	ds_read_b32 v34, v28 offset:6912
	s_or_b64 exec, exec, s[0:1]
	v_or_b32_e32 v29, 0x700, v16
	v_cmp_gt_u32_e32 vcc, s72, v29
	v_mov_b32_e32 v32, 0
	v_mov_b32_e32 v33, 0
	s_and_saveexec_b64 s[0:1], vcc
	ds_read_b32 v33, v28 offset:7168
	s_or_b64 exec, exec, s[0:1]
	v_or_b32_e32 v29, 0x740, v16
	v_cmp_gt_u32_e32 vcc, s72, v29
	s_and_saveexec_b64 s[0:1], vcc
	ds_read_b32 v32, v28 offset:7424
	s_or_b64 exec, exec, s[0:1]
	v_or_b32_e32 v29, 0x780, v16
	v_cmp_gt_u32_e32 vcc, s72, v29
	v_mov_b32_e32 v29, 0
	v_mov_b32_e32 v31, 0
	s_and_saveexec_b64 s[0:1], vcc
	ds_read_b32 v31, v28 offset:7680
	s_or_b64 exec, exec, s[0:1]
	v_or_b32_e32 v30, 0x7c0, v16
	v_cmp_gt_u32_e32 vcc, s72, v30
	s_and_saveexec_b64 s[0:1], vcc
	ds_read_b32 v29, v28 offset:7936
	s_or_b64 exec, exec, s[0:1]
	s_waitcnt vmcnt(0)
	v_mov_b32_e32 v38, 31
	v_mov_b32_e32 v30, 0
	s_waitcnt lgkmcnt(0)
	v_max_u32_e32 v112, v26, v27
	v_max3_u32 v112, v112, v24, v25
	v_max3_u32 v112, v112, v22, v23
	v_max3_u32 v112, v112, v20, v21
	v_max3_u32 v112, v112, v18, v19
	v_max3_u32 v112, v112, v14, v15
	v_max3_u32 v112, v112, v12, v13
	v_max3_u32 v112, v112, v10, v11
	v_max3_u32 v112, v112, v8, v9
	v_max3_u32 v112, v112, v6, v7
	v_max3_u32 v112, v112, v4, v5
	v_max3_u32 v112, v112, v2, v3
	v_max3_u32 v112, v112, v37, v36
	v_max3_u32 v112, v112, v35, v34
	v_max3_u32 v112, v112, v33, v32
	v_max3_u32 v112, v112, v31, v29
	s_nop 1
	v_max_u32_dpp v112, v112, v112 quad_perm:[1,0,3,2] row_mask:0xf bank_mask:0xf
	s_nop 1
	v_max_u32_dpp v112, v112, v112 quad_perm:[2,3,0,1] row_mask:0xf bank_mask:0xf
	s_nop 1
	v_max_u32_dpp v112, v112, v112 row_half_mirror row_mask:0xf bank_mask:0xf
	s_nop 1
	v_max_u32_dpp v112, v112, v112 row_mirror row_mask:0xf bank_mask:0xf
	s_nop 1
	v_readlane_b32 s98, v112, 0
	v_readlane_b32 s99, v112, 16
	v_readlane_b32 s100, v112, 32
	v_readlane_b32 s101, v112, 48
	s_max_u32 s98, s98, s99
	s_max_u32 s100, s100, s101
	s_max_u32 s98, s98, s100
	s_lshr_b32 s98, s98, 23
	s_mov_b32 s99, 0
.Lp1_32:
	s_lshl_b32 s100, s98, 23
	v_mov_b32_e32 v39, s100
	v_cmp_ge_u32_e32 vcc, v26, v39
	s_bcnt1_i32_b64 s0, vcc
	v_cmp_ge_u32_e32 vcc, v27, v39
	s_bcnt1_i32_b64 s1, vcc
	v_cmp_ge_u32_e32 vcc, v24, v39
	s_add_i32 s0, s1, s0
	s_bcnt1_i32_b64 s1, vcc
	v_cmp_ge_u32_e32 vcc, v25, v39
	s_add_i32 s0, s0, s1
	s_bcnt1_i32_b64 s1, vcc
	v_cmp_ge_u32_e32 vcc, v22, v39
	s_add_i32 s0, s0, s1
	s_bcnt1_i32_b64 s1, vcc
	v_cmp_ge_u32_e32 vcc, v23, v39
	s_add_i32 s0, s0, s1
	s_bcnt1_i32_b64 s1, vcc
	v_cmp_ge_u32_e32 vcc, v20, v39
	s_add_i32 s0, s0, s1
	s_bcnt1_i32_b64 s1, vcc
	v_cmp_ge_u32_e32 vcc, v21, v39
	s_add_i32 s0, s0, s1
	s_bcnt1_i32_b64 s1, vcc
	v_cmp_ge_u32_e32 vcc, v18, v39
	s_add_i32 s0, s0, s1
	s_bcnt1_i32_b64 s1, vcc
	v_cmp_ge_u32_e32 vcc, v19, v39
	s_add_i32 s0, s0, s1
	s_bcnt1_i32_b64 s1, vcc
	v_cmp_ge_u32_e32 vcc, v14, v39
	s_add_i32 s0, s0, s1
	s_bcnt1_i32_b64 s1, vcc
	v_cmp_ge_u32_e32 vcc, v15, v39
	s_add_i32 s0, s0, s1
	s_bcnt1_i32_b64 s1, vcc
	v_cmp_ge_u32_e32 vcc, v12, v39
	s_add_i32 s0, s0, s1
	s_bcnt1_i32_b64 s1, vcc
	v_cmp_ge_u32_e32 vcc, v13, v39
	s_add_i32 s0, s0, s1
	s_bcnt1_i32_b64 s1, vcc
	v_cmp_ge_u32_e32 vcc, v10, v39
	s_add_i32 s0, s0, s1
	s_bcnt1_i32_b64 s1, vcc
	v_cmp_ge_u32_e32 vcc, v11, v39
	s_add_i32 s0, s0, s1
	s_bcnt1_i32_b64 s1, vcc
	v_cmp_ge_u32_e32 vcc, v8, v39
	s_add_i32 s0, s0, s1
	s_bcnt1_i32_b64 s1, vcc
	v_cmp_ge_u32_e32 vcc, v9, v39
	s_add_i32 s0, s0, s1
	s_bcnt1_i32_b64 s1, vcc
	v_cmp_ge_u32_e32 vcc, v6, v39
	s_add_i32 s0, s0, s1
	s_bcnt1_i32_b64 s1, vcc
	v_cmp_ge_u32_e32 vcc, v7, v39
	s_add_i32 s0, s0, s1
	s_bcnt1_i32_b64 s1, vcc
	v_cmp_ge_u32_e32 vcc, v4, v39
	s_add_i32 s0, s0, s1
	s_bcnt1_i32_b64 s1, vcc
	v_cmp_ge_u32_e32 vcc, v5, v39
	s_add_i32 s0, s0, s1
	s_bcnt1_i32_b64 s1, vcc
	v_cmp_ge_u32_e32 vcc, v2, v39
	s_add_i32 s0, s0, s1
	s_bcnt1_i32_b64 s1, vcc
	v_cmp_ge_u32_e32 vcc, v3, v39
	s_add_i32 s0, s0, s1
	s_bcnt1_i32_b64 s1, vcc
	v_cmp_ge_u32_e32 vcc, v37, v39
	s_add_i32 s0, s0, s1
	s_bcnt1_i32_b64 s1, vcc
	v_cmp_ge_u32_e32 vcc, v36, v39
	s_add_i32 s0, s0, s1
	s_bcnt1_i32_b64 s1, vcc
	v_cmp_ge_u32_e32 vcc, v35, v39
	s_add_i32 s0, s0, s1
	s_bcnt1_i32_b64 s1, vcc
	v_cmp_ge_u32_e32 vcc, v34, v39
	s_add_i32 s0, s0, s1
	s_bcnt1_i32_b64 s1, vcc
	v_cmp_ge_u32_e32 vcc, v33, v39
	s_add_i32 s0, s0, s1
	s_bcnt1_i32_b64 s1, vcc
	v_cmp_ge_u32_e32 vcc, v32, v39
	s_add_i32 s0, s0, s1
	s_bcnt1_i32_b64 s1, vcc
	v_cmp_ge_u32_e32 vcc, v31, v39
	s_add_i32 s0, s0, s1
	s_bcnt1_i32_b64 s1, vcc
	v_cmp_ge_u32_e32 vcc, v29, v39
	s_add_i32 s0, s0, s1
	s_bcnt1_i32_b64 s1, vcc
	s_add_i32 s2, s0, s1
	s_cmpk_lt_u32 s2, 0x100
	s_cbranch_scc0 .Lp1_found_32
	s_add_u32 s99, s99, 1
	s_cmp_eq_u32 s98, 0
	s_cbranch_scc1 .LBB0_910
	s_sub_u32 s98, s98, 1
	s_cmp_lt_u32 s99, 4
	s_cbranch_scc1 .Lp1_32
	s_branch .LBB0_910
.Lp1_found_32:
	v_mov_b32_e32 v30, v39
	v_mov_b32_e32 v38, 22
	s_cmpk_eq_i32 s2, 0x100
	s_cbranch_scc1 .Lp1_exit_32

.Lp1_exit_32:
	s_cmpk_eq_i32 s2, 0x100
	s_cbranch_scc1 .Lselfast_32
	v_cmp_gt_u32_e32 vcc, v26, v30
	s_bcnt1_i32_b64 s8, vcc
	v_cmp_gt_u32_e32 vcc, v27, v30
	s_bcnt1_i32_b64 s9, vcc
	v_cmp_gt_u32_e32 vcc, v24, v30
	s_bcnt1_i32_b64 s10, vcc
	v_cmp_gt_u32_e32 vcc, v25, v30
	s_add_i32 s8, s8, s9
	s_bcnt1_i32_b64 s11, vcc
	v_cmp_gt_u32_e32 vcc, v22, v30
	s_add_i32 s8, s8, s10
	s_bcnt1_i32_b64 s64, vcc
	v_cmp_gt_u32_e32 vcc, v23, v30
	s_add_i32 s8, s8, s11
	s_bcnt1_i32_b64 s65, vcc
	v_cmp_gt_u32_e32 vcc, v20, v30
	s_add_i32 s8, s8, s64
	s_bcnt1_i32_b64 s66, vcc
	v_cmp_gt_u32_e32 vcc, v21, v30
	s_add_i32 s8, s8, s65
	s_bcnt1_i32_b64 s67, vcc
	v_cmp_gt_u32_e32 vcc, v18, v30
	s_add_i32 s64, s8, s66
	s_bcnt1_i32_b64 s68, vcc
	v_cmp_gt_u32_e32 vcc, v19, v30
	s_add_i32 s64, s64, s67
	s_bcnt1_i32_b64 s69, vcc
	v_cmp_gt_u32_e32 vcc, v14, v30
	s_add_i32 s64, s64, s68
	s_bcnt1_i32_b64 s73, vcc
	v_cmp_gt_u32_e32 vcc, v15, v30
	s_add_i32 s64, s64, s69
	s_bcnt1_i32_b64 s74, vcc
	v_cmp_gt_u32_e32 vcc, v12, v30
	s_add_i32 s64, s64, s73
	s_bcnt1_i32_b64 s75, vcc
	v_cmp_gt_u32_e32 vcc, v13, v30
	s_add_i32 s64, s64, s74
	s_bcnt1_i32_b64 s76, vcc
	v_cmp_gt_u32_e32 vcc, v10, v30
	s_add_i32 s64, s64, s75
	s_bcnt1_i32_b64 s77, vcc
	v_cmp_gt_u32_e32 vcc, v11, v30
	s_add_i32 s64, s64, s76
	s_bcnt1_i32_b64 s78, vcc
	v_cmp_gt_u32_e32 vcc, v8, v30
	s_add_i32 s64, s64, s77
	s_bcnt1_i32_b64 s79, vcc
	v_cmp_gt_u32_e32 vcc, v9, v30
	s_add_i32 s64, s64, s78
	s_bcnt1_i32_b64 s80, vcc
	v_cmp_gt_u32_e32 vcc, v6, v30
	s_add_i32 s64, s64, s79
	s_bcnt1_i32_b64 s81, vcc
	v_cmp_gt_u32_e32 vcc, v7, v30
	s_add_i32 s64, s64, s80
	s_bcnt1_i32_b64 s82, vcc
	v_cmp_gt_u32_e32 vcc, v4, v30
	s_add_i32 s64, s64, s81
	s_bcnt1_i32_b64 s83, vcc
	v_cmp_gt_u32_e32 vcc, v5, v30
	s_add_i32 s64, s64, s82
	s_bcnt1_i32_b64 s84, vcc
	v_cmp_gt_u32_e32 vcc, v2, v30
	s_add_i32 s64, s64, s83
	s_bcnt1_i32_b64 s85, vcc
	v_cmp_gt_u32_e32 vcc, v3, v30
	s_add_i32 s64, s64, s84
	s_bcnt1_i32_b64 s86, vcc
	v_cmp_gt_u32_e32 vcc, v37, v30
	s_add_i32 s64, s64, s85
	s_bcnt1_i32_b64 s87, vcc
	v_cmp_gt_u32_e32 vcc, v36, v30
	s_add_i32 s64, s64, s86
	s_bcnt1_i32_b64 s88, vcc
	v_cmp_gt_u32_e32 vcc, v35, v30
	s_add_i32 s64, s64, s87
	s_bcnt1_i32_b64 s89, vcc
	v_cmp_gt_u32_e32 vcc, v34, v30
	s_add_i32 s64, s64, s88
	s_bcnt1_i32_b64 s90, vcc
	v_cmp_gt_u32_e32 vcc, v33, v30
	s_add_i32 s64, s64, s89
	s_bcnt1_i32_b64 s91, vcc
	v_cmp_gt_u32_e32 vcc, v32, v30
	s_add_i32 s64, s64, s90
	s_bcnt1_i32_b64 s92, vcc
	v_cmp_gt_u32_e32 vcc, v31, v30
	s_add_i32 s64, s64, s91
	s_bcnt1_i32_b64 s93, vcc
	v_cmp_gt_u32_e32 vcc, v29, v30
	s_add_i32 s64, s64, s92
	s_bcnt1_i32_b64 s94, vcc
	s_add_i32 s64, s64, s93
	s_add_i32 s64, s64, s94
	v_cmp_le_u32_e64 s[62:63], v26, v30
	v_cmp_le_u32_e64 s[60:61], v27, v30
	v_cmp_le_u32_e64 s[58:59], v24, v30
	v_cmp_le_u32_e64 s[56:57], v25, v30
	v_cmp_le_u32_e64 s[54:55], v22, v30
	v_cmp_le_u32_e64 s[52:53], v23, v30
	v_cmp_le_u32_e64 s[50:51], v20, v30
	v_cmp_le_u32_e64 s[48:49], v21, v30
	v_cmp_le_u32_e64 s[46:47], v18, v30
	v_cmp_le_u32_e64 s[44:45], v19, v30
	v_cmp_le_u32_e64 s[42:43], v14, v30
	v_cmp_le_u32_e64 s[40:41], v15, v30
	v_cmp_le_u32_e64 s[38:39], v12, v30
	v_cmp_le_u32_e64 s[36:37], v13, v30
	v_cmp_le_u32_e64 s[34:35], v10, v30
	v_cmp_le_u32_e64 s[30:31], v11, v30
	v_cmp_le_u32_e64 s[28:29], v8, v30
	v_cmp_le_u32_e64 s[26:27], v9, v30
	v_cmp_le_u32_e64 s[24:25], v6, v30
	v_cmp_le_u32_e64 s[22:23], v7, v30
	v_cmp_le_u32_e64 s[4:5], v4, v30
	v_cmp_le_u32_e64 s[0:1], v5, v30
	v_cmp_le_u32_e64 s[2:3], v2, v30
	v_cmp_le_u32_e64 s[6:7], v3, v30
	v_cmp_le_u32_e64 s[20:21], v37, v30
	v_cmp_le_u32_e64 s[18:19], v36, v30
	v_cmp_le_u32_e64 s[16:17], v35, v30
	v_cmp_le_u32_e64 s[14:15], v34, v30
	v_cmp_le_u32_e64 s[12:13], v33, v30
	v_cmp_le_u32_e64 s[10:11], v32, v30
	v_cmp_le_u32_e64 s[8:9], v31, v30
	v_cmp_le_u32_e32 vcc, v29, v30
	s_sub_i32 s73, 0x100, s64
	v_cmp_eq_u32_e64 s[64:65], v26, v30
	s_mov_b64 s[68:69], -1
	s_and_saveexec_b64 s[66:67], s[62:63]
	v_mbcnt_lo_u32_b32 v26, s64, 0
	v_mbcnt_hi_u32_b32 v26, s65, v26
	v_cmp_gt_i32_e64 s[62:63], s73, v26
	s_and_b64 s[62:63], s[64:65], s[62:63]
	s_orn2_b64 s[68:69], s[62:63], exec
	s_or_b64 exec, exec, s[66:67]
	v_cndmask_b32_e64 v26, 0, 1, s[68:69]
	v_cmp_eq_u32_e64 s[66:67], 0, v16
	v_cmp_ne_u32_e64 s[68:69], 0, v26
	s_and_saveexec_b64 s[62:63], s[66:67]
	s_cbranch_execz .LBB0_915
	v_mov_b64_e32 v[38:39], s[68:69]
	global_store_dwordx2 v[0:1], v[38:39], off

.LBB0_1044:
	s_mov_b64 s[66:67], 0
	s_mov_b64 s[2:3], 0xf8
	s_cbranch_execz .LBB0_1158
	ds_read2st64_b32 v[18:19], v28 offset1:1
	ds_read2st64_b32 v[14:15], v28 offset0:2 offset1:3
	ds_read2st64_b32 v[12:13], v28 offset0:4 offset1:5
	ds_read2st64_b32 v[10:11], v28 offset0:6 offset1:7
	ds_read2st64_b32 v[8:9], v28 offset0:8 offset1:9
	ds_read2st64_b32 v[6:7], v28 offset0:10 offset1:11
	ds_read2st64_b32 v[4:5], v28 offset0:12 offset1:13
	ds_read2st64_b32 v[2:3], v28 offset0:14 offset1:15
	v_or_b32_e32 v20, 0x400, v16
	v_cmp_gt_u32_e32 vcc, s72, v20
	v_mov_b32_e32 v27, 0
	v_mov_b32_e32 v29, 0
	s_and_saveexec_b64 s[0:1], vcc
	ds_read_b32 v29, v28 offset:4096
	s_or_b64 exec, exec, s[0:1]
	v_or_b32_e32 v20, 0x440, v16
	v_cmp_gt_u32_e32 vcc, s72, v20
	s_and_saveexec_b64 s[0:1], vcc
	ds_read_b32 v27, v28 offset:4352
	s_or_b64 exec, exec, s[0:1]
	v_or_b32_e32 v20, 0x480, v16
	v_cmp_gt_u32_e32 vcc, s72, v20
	v_mov_b32_e32 v25, 0
	v_mov_b32_e32 v26, 0
	s_and_saveexec_b64 s[0:1], vcc
	ds_read_b32 v26, v28 offset:4608
	s_or_b64 exec, exec, s[0:1]
	v_or_b32_e32 v20, 0x4c0, v16
	v_cmp_gt_u32_e32 vcc, s72, v20
	s_and_saveexec_b64 s[0:1], vcc
	ds_read_b32 v25, v28 offset:4864
	s_or_b64 exec, exec, s[0:1]
	v_or_b32_e32 v20, 0x500, v16
	v_cmp_gt_u32_e32 vcc, s72, v20
	v_mov_b32_e32 v23, 0
	v_mov_b32_e32 v24, 0
	s_and_saveexec_b64 s[0:1], vcc
	ds_read_b32 v24, v28 offset:5120
	s_or_b64 exec, exec, s[0:1]
	v_or_b32_e32 v20, 0x540, v16
	v_cmp_gt_u32_e32 vcc, s72, v20
	s_and_saveexec_b64 s[0:1], vcc
	ds_read_b32 v23, v28 offset:5376
	s_or_b64 exec, exec, s[0:1]
	v_or_b32_e32 v20, 0x580, v16
	v_cmp_gt_u32_e32 vcc, s72, v20
	v_mov_b32_e32 v20, 0
	v_mov_b32_e32 v22, 0
	s_and_saveexec_b64 s[0:1], vcc
	ds_read_b32 v22, v28 offset:5632
	s_or_b64 exec, exec, s[0:1]
	v_or_b32_e32 v21, 0x5c0, v16
	v_cmp_gt_u32_e32 vcc, s72, v21
	s_and_saveexec_b64 s[0:1], vcc
	ds_read_b32 v20, v28 offset:5888
	s_or_b64 exec, exec, s[0:1]
	s_waitcnt vmcnt(2)
	v_mov_b32_e32 v30, 31
	v_mov_b32_e32 v21, 0
	s_waitcnt lgkmcnt(0)
	v_max_u32_e32 v112, v18, v19
	v_max3_u32 v112, v112, v14, v15
	v_max3_u32 v112, v112, v12, v13
	v_max3_u32 v112, v112, v10, v11
	v_max3_u32 v112, v112, v8, v9
	v_max3_u32 v112, v112, v6, v7
	v_max3_u32 v112, v112, v4, v5
	v_max3_u32 v112, v112, v2, v3
	v_max3_u32 v112, v112, v29, v27
	v_max3_u32 v112, v112, v26, v25
	v_max3_u32 v112, v112, v24, v23
	v_max3_u32 v112, v112, v22, v20
	s_nop 1
	v_max_u32_dpp v112, v112, v112 quad_perm:[1,0,3,2] row_mask:0xf bank_mask:0xf
	s_nop 1
	v_max_u32_dpp v112, v112, v112 quad_perm:[2,3,0,1] row_mask:0xf bank_mask:0xf
	s_nop 1
	v_max_u32_dpp v112, v112, v112 row_half_mirror row_mask:0xf bank_mask:0xf
	s_nop 1
	v_max_u32_dpp v112, v112, v112 row_mirror row_mask:0xf bank_mask:0xf
	s_nop 1
	v_readlane_b32 s98, v112, 0
	v_readlane_b32 s99, v112, 16
	v_readlane_b32 s100, v112, 32
	v_readlane_b32 s101, v112, 48
	s_max_u32 s98, s98, s99
	s_max_u32 s100, s100, s101
	s_max_u32 s98, s98, s100
	s_lshr_b32 s98, s98, 23
	s_mov_b32 s99, 0
.Lp1_24:
	s_lshl_b32 s100, s98, 23
	v_mov_b32_e32 v31, s100
	v_cmp_ge_u32_e32 vcc, v18, v31
	s_bcnt1_i32_b64 s0, vcc
	v_cmp_ge_u32_e32 vcc, v19, v31
	s_bcnt1_i32_b64 s1, vcc
	v_cmp_ge_u32_e32 vcc, v14, v31
	s_add_i32 s0, s1, s0
	s_bcnt1_i32_b64 s1, vcc
	v_cmp_ge_u32_e32 vcc, v15, v31
	s_add_i32 s0, s0, s1
	s_bcnt1_i32_b64 s1, vcc
	v_cmp_ge_u32_e32 vcc, v12, v31
	s_add_i32 s0, s0, s1
	s_bcnt1_i32_b64 s1, vcc
	v_cmp_ge_u32_e32 vcc, v13, v31
	s_add_i32 s0, s0, s1
	s_bcnt1_i32_b64 s1, vcc
	v_cmp_ge_u32_e32 vcc, v10, v31
	s_add_i32 s0, s0, s1
	s_bcnt1_i32_b64 s1, vcc
	v_cmp_ge_u32_e32 vcc, v11, v31
	s_add_i32 s0, s0, s1
	s_bcnt1_i32_b64 s1, vcc
	v_cmp_ge_u32_e32 vcc, v8, v31
	s_add_i32 s0, s0, s1
	s_bcnt1_i32_b64 s1, vcc
	v_cmp_ge_u32_e32 vcc, v9, v31
	s_add_i32 s0, s0, s1
	s_bcnt1_i32_b64 s1, vcc
	v_cmp_ge_u32_e32 vcc, v6, v31
	s_add_i32 s0, s0, s1
	s_bcnt1_i32_b64 s1, vcc
	v_cmp_ge_u32_e32 vcc, v7, v31
	s_add_i32 s0, s0, s1
	s_bcnt1_i32_b64 s1, vcc
	v_cmp_ge_u32_e32 vcc, v4, v31
	s_add_i32 s0, s0, s1
	s_bcnt1_i32_b64 s1, vcc
	v_cmp_ge_u32_e32 vcc, v5, v31
	s_add_i32 s0, s0, s1
	s_bcnt1_i32_b64 s1, vcc
	v_cmp_ge_u32_e32 vcc, v2, v31
	s_add_i32 s0, s0, s1
	s_bcnt1_i32_b64 s1, vcc
	v_cmp_ge_u32_e32 vcc, v3, v31
	s_add_i32 s0, s0, s1
	s_bcnt1_i32_b64 s1, vcc
	v_cmp_ge_u32_e32 vcc, v29, v31
	s_add_i32 s0, s0, s1
	s_bcnt1_i32_b64 s1, vcc
	v_cmp_ge_u32_e32 vcc, v27, v31
	s_add_i32 s0, s0, s1
	s_bcnt1_i32_b64 s1, vcc
	v_cmp_ge_u32_e32 vcc, v26, v31
	s_add_i32 s0, s0, s1
	s_bcnt1_i32_b64 s1, vcc
	v_cmp_ge_u32_e32 vcc, v25, v31
	s_add_i32 s0, s0, s1
	s_bcnt1_i32_b64 s1, vcc
	v_cmp_ge_u32_e32 vcc, v24, v31
	s_add_i32 s0, s0, s1
	s_bcnt1_i32_b64 s1, vcc
	v_cmp_ge_u32_e32 vcc, v23, v31
	s_add_i32 s0, s0, s1
	s_bcnt1_i32_b64 s1, vcc
	v_cmp_ge_u32_e32 vcc, v22, v31
	s_add_i32 s0, s0, s1
	s_bcnt1_i32_b64 s1, vcc
	v_cmp_ge_u32_e32 vcc, v20, v31
	s_add_i32 s0, s0, s1
	s_bcnt1_i32_b64 s1, vcc
	s_add_i32 s2, s0, s1
	s_cmpk_lt_u32 s2, 0x100
	s_cbranch_scc0 .Lp1_found_24
	s_add_u32 s99, s99, 1
	s_cmp_eq_u32 s98, 0
	s_cbranch_scc1 .LBB0_1062
	s_sub_u32 s98, s98, 1
	s_cmp_lt_u32 s99, 4
	s_cbranch_scc1 .Lp1_24
	s_branch .LBB0_1062
.Lp1_found_24:
	v_mov_b32_e32 v21, v31
	v_mov_b32_e32 v30, 22
	s_cmpk_eq_i32 s2, 0x100
	s_cbranch_scc1 .Lp1_exit_24

.Lp1_exit_24:
	s_cmpk_eq_i32 s2, 0x100
	s_cbranch_scc1 .Lselfast_24
	v_cmp_gt_u32_e32 vcc, v18, v21
	s_bcnt1_i32_b64 s50, vcc
	v_cmp_gt_u32_e32 vcc, v19, v21
	s_bcnt1_i32_b64 s51, vcc
	v_cmp_gt_u32_e32 vcc, v14, v21
	v_cmp_gt_u32_e64 s[48:49], v20, v21
	s_bcnt1_i32_b64 s52, vcc
	v_cmp_gt_u32_e32 vcc, v15, v21
	s_bcnt1_i32_b64 s48, s[48:49]
	s_add_i32 s49, s50, s51
	s_bcnt1_i32_b64 s53, vcc
	v_cmp_gt_u32_e32 vcc, v12, v21
	s_add_i32 s49, s49, s52
	s_bcnt1_i32_b64 s54, vcc
	v_cmp_gt_u32_e32 vcc, v13, v21
	s_add_i32 s49, s49, s53
	s_bcnt1_i32_b64 s55, vcc
	v_cmp_gt_u32_e32 vcc, v10, v21
	s_add_i32 s49, s49, s54
	s_bcnt1_i32_b64 s56, vcc
	v_cmp_gt_u32_e32 vcc, v11, v21
	s_add_i32 s49, s49, s55
	s_bcnt1_i32_b64 s57, vcc
	v_cmp_gt_u32_e32 vcc, v8, v21
	s_add_i32 s49, s49, s56
	s_bcnt1_i32_b64 s58, vcc
	v_cmp_gt_u32_e32 vcc, v9, v21
	s_add_i32 s49, s49, s57
	s_bcnt1_i32_b64 s59, vcc
	v_cmp_gt_u32_e32 vcc, v6, v21
	s_add_i32 s49, s49, s58
	s_bcnt1_i32_b64 s60, vcc
	v_cmp_gt_u32_e32 vcc, v7, v21
	s_add_i32 s49, s49, s59
	s_bcnt1_i32_b64 s61, vcc
	v_cmp_gt_u32_e32 vcc, v4, v21
	s_add_i32 s49, s49, s60
	s_bcnt1_i32_b64 s62, vcc
	v_cmp_gt_u32_e32 vcc, v5, v21
	s_add_i32 s49, s49, s61
	s_bcnt1_i32_b64 s63, vcc
	v_cmp_gt_u32_e32 vcc, v2, v21
	s_add_i32 s49, s49, s62
	s_bcnt1_i32_b64 s64, vcc
	v_cmp_gt_u32_e32 vcc, v3, v21
	s_add_i32 s49, s49, s63
	s_bcnt1_i32_b64 s65, vcc
	v_cmp_gt_u32_e32 vcc, v29, v21
	s_add_i32 s49, s49, s64
	s_bcnt1_i32_b64 s66, vcc
	v_cmp_gt_u32_e32 vcc, v27, v21
	s_add_i32 s49, s49, s65
	s_bcnt1_i32_b64 s67, vcc
	v_cmp_gt_u32_e32 vcc, v26, v21
	s_add_i32 s49, s49, s66
	s_bcnt1_i32_b64 s68, vcc
	v_cmp_gt_u32_e32 vcc, v25, v21
	s_add_i32 s49, s49, s67
	s_bcnt1_i32_b64 s69, vcc
	v_cmp_gt_u32_e32 vcc, v24, v21
	s_add_i32 s49, s49, s68
	s_bcnt1_i32_b64 s73, vcc
	v_cmp_gt_u32_e32 vcc, v23, v21
	s_add_i32 s49, s49, s69
	s_bcnt1_i32_b64 s74, vcc
	v_cmp_gt_u32_e32 vcc, v22, v21
	s_add_i32 s49, s49, s73
	s_bcnt1_i32_b64 s75, vcc
	s_add_i32 s49, s49, s74
	s_add_i32 s49, s49, s75
	s_add_i32 s49, s49, s48
	v_cmp_le_u32_e64 s[46:47], v18, v21
	v_cmp_le_u32_e64 s[44:45], v19, v21
	v_cmp_le_u32_e64 s[42:43], v14, v21
	v_cmp_le_u32_e64 s[40:41], v15, v21
	v_cmp_le_u32_e64 s[38:39], v12, v21
	v_cmp_le_u32_e64 s[36:37], v13, v21
	v_cmp_le_u32_e64 s[34:35], v10, v21
	v_cmp_le_u32_e64 s[30:31], v11, v21
	v_cmp_le_u32_e64 s[28:29], v8, v21
	v_cmp_le_u32_e64 s[26:27], v9, v21
	v_cmp_le_u32_e64 s[24:25], v6, v21
	v_cmp_le_u32_e64 s[22:23], v7, v21
	v_cmp_le_u32_e64 s[20:21], v4, v21
	v_cmp_le_u32_e64 s[18:19], v5, v21
	v_cmp_le_u32_e64 s[16:17], v2, v21
	v_cmp_le_u32_e64 s[14:15], v3, v21
	v_cmp_le_u32_e64 s[12:13], v29, v21
	v_cmp_le_u32_e64 s[10:11], v27, v21
	v_cmp_le_u32_e64 s[8:9], v26, v21
	v_cmp_le_u32_e64 s[6:7], v25, v21
	v_cmp_le_u32_e64 s[4:5], v24, v21
	v_cmp_le_u32_e64 s[2:3], v23, v21
	v_cmp_le_u32_e64 s[0:1], v22, v21
	v_cmp_le_u32_e32 vcc, v20, v21
	s_sub_i32 s54, 0x100, s49
	v_cmp_eq_u32_e64 s[48:49], v18, v21
	s_mov_b64 s[52:53], -1
	s_and_saveexec_b64 s[50:51], s[46:47]
	v_mbcnt_lo_u32_b32 v18, s48, 0
	v_mbcnt_hi_u32_b32 v18, s49, v18
	v_cmp_gt_i32_e64 s[46:47], s54, v18
	s_and_b64 s[46:47], s[48:49], s[46:47]
	s_orn2_b64 s[52:53], s[46:47], exec
	s_or_b64 exec, exec, s[50:51]
	v_cndmask_b32_e64 v18, 0, 1, s[52:53]
	v_cmp_eq_u32_e64 s[66:67], 0, v16
	v_cmp_ne_u32_e64 s[50:51], 0, v18
	s_and_saveexec_b64 s[46:47], s[66:67]
	s_cbranch_execz .LBB0_1067
	v_mov_b64_e32 v[30:31], s[50:51]
	global_store_dwordx2 v[0:1], v[30:31], off

.LBB0_1159:
	ds_read2st64_b32 v[8:9], v28 offset1:1
	ds_read2st64_b32 v[6:7], v28 offset0:2 offset1:3
	ds_read2st64_b32 v[4:5], v28 offset0:4 offset1:5
	ds_read2st64_b32 v[2:3], v28 offset0:6 offset1:7
	v_or_b32_e32 v10, 0x200, v16
	v_cmp_gt_u32_e32 vcc, s72, v10
	v_mov_b32_e32 v19, 0
	v_mov_b32_e32 v20, 0
	s_and_saveexec_b64 s[0:1], vcc
	ds_read_b32 v20, v28 offset:2048
	s_or_b64 exec, exec, s[0:1]
	v_or_b32_e32 v10, 0x240, v16
	v_cmp_gt_u32_e32 vcc, s72, v10
	s_and_saveexec_b64 s[0:1], vcc
	ds_read_b32 v19, v28 offset:2304
	s_or_b64 exec, exec, s[0:1]
	v_or_b32_e32 v10, 0x280, v16
	v_cmp_gt_u32_e32 vcc, s72, v10
	v_mov_b32_e32 v15, 0
	v_mov_b32_e32 v18, 0
	s_and_saveexec_b64 s[0:1], vcc
	ds_read_b32 v18, v28 offset:2560
	s_or_b64 exec, exec, s[0:1]
	v_or_b32_e32 v10, 0x2c0, v16
	v_cmp_gt_u32_e32 vcc, s72, v10
	s_and_saveexec_b64 s[0:1], vcc
	ds_read_b32 v15, v28 offset:2816
	s_or_b64 exec, exec, s[0:1]
	v_or_b32_e32 v10, 0x300, v16
	v_cmp_gt_u32_e32 vcc, s72, v10
	v_mov_b32_e32 v13, 0
	v_mov_b32_e32 v14, 0
	s_and_saveexec_b64 s[0:1], vcc
	ds_read_b32 v14, v28 offset:3072
	s_or_b64 exec, exec, s[0:1]
	v_or_b32_e32 v10, 0x340, v16
	v_cmp_gt_u32_e32 vcc, s72, v10
	s_and_saveexec_b64 s[0:1], vcc
	ds_read_b32 v13, v28 offset:3328
	s_or_b64 exec, exec, s[0:1]
	v_or_b32_e32 v10, 0x380, v16
	v_cmp_gt_u32_e32 vcc, s72, v10
	v_mov_b32_e32 v10, 0
	v_mov_b32_e32 v12, 0
	s_and_saveexec_b64 s[0:1], vcc
	ds_read_b32 v12, v28 offset:3584
	s_or_b64 exec, exec, s[0:1]
	v_or_b32_e32 v11, 0x3c0, v16
	v_cmp_gt_u32_e32 vcc, s72, v11
	s_and_saveexec_b64 s[0:1], vcc
	ds_read_b32 v10, v28 offset:3840
	s_or_b64 exec, exec, s[0:1]
	v_mov_b32_e32 v21, 31
	v_mov_b32_e32 v11, 0
	s_waitcnt lgkmcnt(0)
	v_max_u32_e32 v112, v8, v9
	v_max3_u32 v112, v112, v6, v7
	v_max3_u32 v112, v112, v4, v5
	v_max3_u32 v112, v112, v2, v3
	v_max3_u32 v112, v112, v20, v19
	v_max3_u32 v112, v112, v18, v15
	v_max3_u32 v112, v112, v14, v13
	v_max3_u32 v112, v112, v12, v10
	s_nop 1
	v_max_u32_dpp v112, v112, v112 quad_perm:[1,0,3,2] row_mask:0xf bank_mask:0xf
	s_nop 1
	v_max_u32_dpp v112, v112, v112 quad_perm:[2,3,0,1] row_mask:0xf bank_mask:0xf
	s_nop 1
	v_max_u32_dpp v112, v112, v112 row_half_mirror row_mask:0xf bank_mask:0xf
	s_nop 1
	v_max_u32_dpp v112, v112, v112 row_mirror row_mask:0xf bank_mask:0xf
	s_nop 1
	v_readlane_b32 s98, v112, 0
	v_readlane_b32 s99, v112, 16
	v_readlane_b32 s100, v112, 32
	v_readlane_b32 s101, v112, 48
	s_max_u32 s98, s98, s99
	s_max_u32 s100, s100, s101
	s_max_u32 s98, s98, s100
	s_lshr_b32 s98, s98, 23
	s_mov_b32 s99, 0
.Lp1_16:
	s_lshl_b32 s100, s98, 23
	v_mov_b32_e32 v22, s100
	v_cmp_ge_u32_e32 vcc, v8, v22
	s_bcnt1_i32_b64 s0, vcc
	v_cmp_ge_u32_e32 vcc, v9, v22
	s_bcnt1_i32_b64 s1, vcc
	v_cmp_ge_u32_e32 vcc, v6, v22
	s_add_i32 s0, s1, s0
	s_bcnt1_i32_b64 s1, vcc
	v_cmp_ge_u32_e32 vcc, v7, v22
	s_add_i32 s0, s0, s1
	s_bcnt1_i32_b64 s1, vcc
	v_cmp_ge_u32_e32 vcc, v4, v22
	s_add_i32 s0, s0, s1
	s_bcnt1_i32_b64 s1, vcc
	v_cmp_ge_u32_e32 vcc, v5, v22
	s_add_i32 s0, s0, s1
	s_bcnt1_i32_b64 s1, vcc
	v_cmp_ge_u32_e32 vcc, v2, v22
	s_add_i32 s0, s0, s1
	s_bcnt1_i32_b64 s1, vcc
	v_cmp_ge_u32_e32 vcc, v3, v22
	s_add_i32 s0, s0, s1
	s_bcnt1_i32_b64 s1, vcc
	v_cmp_ge_u32_e32 vcc, v20, v22
	s_add_i32 s0, s0, s1
	s_bcnt1_i32_b64 s1, vcc
	v_cmp_ge_u32_e32 vcc, v19, v22
	s_add_i32 s0, s0, s1
	s_bcnt1_i32_b64 s1, vcc
	v_cmp_ge_u32_e32 vcc, v18, v22
	s_add_i32 s0, s0, s1
	s_bcnt1_i32_b64 s1, vcc
	v_cmp_ge_u32_e32 vcc, v15, v22
	s_add_i32 s0, s0, s1
	s_bcnt1_i32_b64 s1, vcc
	v_cmp_ge_u32_e32 vcc, v14, v22
	s_add_i32 s0, s0, s1
	s_bcnt1_i32_b64 s1, vcc
	v_cmp_ge_u32_e32 vcc, v13, v22
	s_add_i32 s0, s0, s1
	s_bcnt1_i32_b64 s1, vcc
	v_cmp_ge_u32_e32 vcc, v12, v22
	s_add_i32 s0, s0, s1
	s_bcnt1_i32_b64 s1, vcc
	v_cmp_ge_u32_e32 vcc, v10, v22
	s_add_i32 s0, s0, s1
	s_bcnt1_i32_b64 s1, vcc
	s_add_i32 s2, s0, s1
	s_cmpk_lt_u32 s2, 0x100
	s_cbranch_scc0 .Lp1_found_16
	s_add_u32 s99, s99, 1
	s_cmp_eq_u32 s98, 0
	s_cbranch_scc1 .LBB0_1176
	s_sub_u32 s98, s98, 1
	s_cmp_lt_u32 s99, 4
	s_cbranch_scc1 .Lp1_16
	s_branch .LBB0_1176
.Lp1_found_16:
	v_mov_b32_e32 v11, v22
	v_mov_b32_e32 v21, 22
	s_cmpk_eq_i32 s2, 0x100
	s_cbranch_scc1 .Lp1_exit_16

.Lp1_exit_16:
	s_cmpk_eq_i32 s2, 0x100
	s_cbranch_scc1 .Lselfast_16
	v_cmp_gt_u32_e32 vcc, v8, v11
	s_bcnt1_i32_b64 s34, vcc
	v_cmp_gt_u32_e32 vcc, v9, v11
	s_bcnt1_i32_b64 s35, vcc
	v_cmp_gt_u32_e32 vcc, v6, v11
	v_cmp_gt_u32_e64 s[28:29], v10, v11
	s_bcnt1_i32_b64 s36, vcc
	v_cmp_gt_u32_e32 vcc, v7, v11
	s_bcnt1_i32_b64 s28, s[28:29]
	s_add_i32 s29, s34, s35
	s_bcnt1_i32_b64 s37, vcc
	v_cmp_gt_u32_e32 vcc, v4, v11
	s_add_i32 s29, s29, s36
	s_bcnt1_i32_b64 s38, vcc
	v_cmp_gt_u32_e32 vcc, v5, v11
	s_add_i32 s29, s29, s37
	s_bcnt1_i32_b64 s39, vcc
	v_cmp_gt_u32_e32 vcc, v2, v11
	s_add_i32 s29, s29, s38
	s_bcnt1_i32_b64 s40, vcc
	v_cmp_gt_u32_e32 vcc, v3, v11
	s_add_i32 s29, s29, s39
	s_bcnt1_i32_b64 s41, vcc
	v_cmp_gt_u32_e32 vcc, v20, v11
	s_add_i32 s29, s29, s40
	s_bcnt1_i32_b64 s42, vcc
	v_cmp_gt_u32_e32 vcc, v19, v11
	s_add_i32 s29, s29, s41
	s_bcnt1_i32_b64 s43, vcc
	v_cmp_gt_u32_e32 vcc, v18, v11
	s_add_i32 s29, s29, s42
	s_bcnt1_i32_b64 s44, vcc
	v_cmp_gt_u32_e32 vcc, v15, v11
	s_add_i32 s29, s29, s43
	s_bcnt1_i32_b64 s45, vcc
	v_cmp_gt_u32_e32 vcc, v14, v11
	s_add_i32 s29, s29, s44
	s_bcnt1_i32_b64 s46, vcc
	v_cmp_gt_u32_e32 vcc, v13, v11
	s_add_i32 s29, s29, s45
	s_bcnt1_i32_b64 s47, vcc
	v_cmp_gt_u32_e32 vcc, v12, v11
	s_add_i32 s29, s29, s46
	s_bcnt1_i32_b64 s48, vcc
	s_add_i32 s29, s29, s47
	s_add_i32 s29, s29, s48
	s_add_i32 s29, s29, s28
	v_cmp_le_u32_e64 s[30:31], v8, v11
	v_cmp_le_u32_e64 s[26:27], v9, v11
	v_cmp_le_u32_e64 s[24:25], v6, v11
	v_cmp_le_u32_e64 s[22:23], v7, v11
	v_cmp_le_u32_e64 s[20:21], v4, v11
	v_cmp_le_u32_e64 s[18:19], v5, v11
	v_cmp_le_u32_e64 s[16:17], v2, v11
	v_cmp_le_u32_e64 s[14:15], v3, v11
	v_cmp_le_u32_e64 s[12:13], v20, v11
	v_cmp_le_u32_e64 s[10:11], v19, v11
	v_cmp_le_u32_e64 s[8:9], v18, v11
	v_cmp_le_u32_e64 s[6:7], v15, v11
	v_cmp_le_u32_e64 s[4:5], v14, v11
	v_cmp_le_u32_e64 s[2:3], v13, v11
	v_cmp_le_u32_e64 s[0:1], v12, v11
	v_cmp_le_u32_e32 vcc, v10, v11
	s_sub_i32 s38, 0x100, s29
	v_cmp_eq_u32_e64 s[28:29], v8, v11
	s_mov_b64 s[36:37], -1
	s_and_saveexec_b64 s[34:35], s[30:31]
	v_mbcnt_lo_u32_b32 v8, s28, 0
	v_mbcnt_hi_u32_b32 v8, s29, v8
	v_cmp_gt_i32_e64 s[30:31], s38, v8
	s_and_b64 s[30:31], s[28:29], s[30:31]
	s_orn2_b64 s[36:37], s[30:31], exec
	s_or_b64 exec, exec, s[34:35]
	v_cndmask_b32_e64 v8, 0, 1, s[36:37]
	v_cmp_eq_u32_e64 s[66:67], 0, v16
	v_cmp_ne_u32_e64 s[34:35], 0, v8
	s_and_saveexec_b64 s[30:31], s[66:67]
	s_cbranch_execz .LBB0_1181
	v_mov_b64_e32 v[22:23], s[34:35]
	global_store_dwordx2 v[0:1], v[22:23], off
